# diff-attention kt-loop second half rewritten by hand: QK of sub-tile 1 issued before PV of sub-tile 0, softmax VALU interleaved into PV MFMA shadow; no precision change
# speedup vs baseline: 1.0049x; 1.0049x over previous
; DI f32x16 mfma32(bf16x8 a, bf16x8 b, f32x16 c) { return __builtin_amdgcn_mfma_f32_32x32x16_bf16(a, b, c, 0, 0, 0); }
; DI bool softmax_tile(f32x16& s0, f32x16& s1, float& m, float& l, float& alpha, bf16x8* pf, int lane, bool first, bool check) {
;   if (first) {
;     float mx = fmaxf(s0[0], s1[0]);
; #pragma unroll
;     for (int i = 1; i < 16; ++i) mx = fmaxf(mx, fmaxf(s0[i], s1[i]));
;     mx = fmaxf(mx, shx(mx, 32, lane));
;     m += mx;
; #pragma unroll
;     for (int i = 0; i < 16; ++i) { s0[i] -= mx; s1[i] -= mx; }
;   }
;   float sum = 0.f;
; #pragma unroll
;   for (int i = 0; i < 16; ++i) { s0[i] = __builtin_amdgcn_exp2f(s0[i]); sum += s0[i]; }
; #pragma unroll
;   for (int i = 0; i < 16; ++i) { s1[i] = __builtin_amdgcn_exp2f(s1[i]); sum += s1[i]; }
;   l += sum;
;   pf[0] = pack8(s0, 0); pf[1] = pack8(s0, 8); pf[2] = pack8(s1, 0); pf[3] = pack8(s1, 8);
;   alpha = 1.f;
;   if (!check) return false;
;   const float rsum = sum + shx(sum, 32, lane);
;   const bool trig = rsum > 65536.f;
;   const bool resc = (__builtin_amdgcn_ballot_w64(trig) != 0ull);
;   alpha = 1.f;
;   if (resc) {
;     const float d = trig ? (float)(__builtin_amdgcn_frexp_expf(rsum) - 7) : 0.f;
;     alpha = __builtin_amdgcn_exp2f(-d);
;     m += d; l *= alpha;
;   }
;   return resc;
; }
; DI void attn_diff_unit(const Params& p, int li, int b, int h, int qb, char* smem, bool pre, int nh, bool has_next) {
;     ...
;       const int kbase = kt * 128 + sub * 64;
;       const int relmin = kbase - (qb * 128 + 127), relmax = kbase + 63 - qb * 128;
;       const float cb = (relmin >= 128) ? cR : ((relmax <= -128) ? cL : 0.f);
;       f32x16 s0, s1;
; #pragma unroll
;       for (int i = 0; i < 16; ++i) { s0[i] = cb - m; s1[i] = cb - m; }
;       {
;         bf16x8 kf[8];
; #pragma unroll
;         for (int s = 0; s < 4; ++s) {
;           kf[2 * s] = *(const bf16x8*)(ks + (sub * 64 + r32) * KR + (map * 64 + s * 16 + hh * 8) * 2);
;           kf[2 * s + 1] = *(const bf16x8*)(ks + (sub * 64 + 32 + r32) * KR + (map * 64 + s * 16 + hh * 8) * 2);
;         }
;         __builtin_amdgcn_sched_barrier(0); __builtin_amdgcn_s_setprio(1);
; #pragma unroll
;         for (int s = 0; s < 4; ++s) { s0 = mfma32(kf[2 * s], qf[s], s0); s1 = mfma32(kf[2 * s + 1], qf[s], s1); }
;       __builtin_amdgcn_s_setprio(0);
; }
.LBB0_572:
	v_add3_u32 v175, s45, v164, v163
	ds_read_b128 v[212:215], v174 offset:17408
	ds_read_b128 v[216:219], v174 offset:26112
	ds_read_b128 v[220:223], v174 offset:17440
	ds_read_b128 v[224:227], v174 offset:26144
	ds_read_b128 v[228:231], v174 offset:17472
	ds_read_b128 v[232:235], v174 offset:26176
	ds_read_b128 v[176:179], v174 offset:17504
	ds_read_b128 v[242:245], v174 offset:26208
	v_add_u32_e32 v236, 0x8800, v175
	v_exp_f32_e32 v80, v80
	v_exp_f32_e32 v81, v81
	v_exp_f32_e32 v82, v82
	v_exp_f32_e32 v83, v83
	v_add_f32_e32 v250, 0, v80
	v_exp_f32_e32 v84, v84
	v_add_f32_e32 v250, v81, v250
	v_exp_f32_e32 v85, v85
	v_add_f32_e32 v250, v82, v250
	v_exp_f32_e32 v86, v86
	v_add_f32_e32 v250, v83, v250
	v_exp_f32_e32 v87, v87
	v_add_f32_e32 v250, v84, v250
	v_exp_f32_e32 v88, v88
	v_add_f32_e32 v250, v85, v250
	v_exp_f32_e32 v89, v89
	v_add_f32_e32 v250, v86, v250
	v_exp_f32_e32 v90, v90
	v_add_f32_e32 v250, v87, v250
	v_exp_f32_e32 v91, v91
	v_add_f32_e32 v250, v88, v250
	v_exp_f32_e32 v92, v92
	v_add_f32_e32 v250, v89, v250
	v_exp_f32_e32 v93, v93
	v_add_f32_e32 v250, v90, v250
	v_exp_f32_e32 v94, v94
	v_add_f32_e32 v250, v91, v250
	v_exp_f32_e32 v95, v95
	v_add_f32_e32 v250, v92, v250
	v_exp_f32_e32 v64, v64
	v_add_f32_e32 v250, v93, v250
	v_exp_f32_e32 v65, v65
	v_add_f32_e32 v250, v94, v250
	v_exp_f32_e32 v66, v66
	v_add_f32_e32 v250, v95, v250
	v_exp_f32_e32 v67, v67
	v_add_f32_e32 v250, v64, v250
	v_exp_f32_e32 v68, v68
	v_add_f32_e32 v250, v65, v250
	v_exp_f32_e32 v69, v69
	v_add_f32_e32 v250, v66, v250
	v_exp_f32_e32 v70, v70
	v_add_f32_e32 v250, v67, v250
	v_exp_f32_e32 v71, v71
	v_add_f32_e32 v250, v68, v250
	v_exp_f32_e32 v72, v72
	v_add_f32_e32 v250, v69, v250
	v_exp_f32_e32 v73, v73
	v_add_f32_e32 v250, v70, v250
	v_exp_f32_e32 v74, v74
	v_add_f32_e32 v250, v71, v250
	v_exp_f32_e32 v75, v75
	v_add_f32_e32 v250, v72, v250
	v_exp_f32_e32 v76, v76
	v_add_f32_e32 v250, v73, v250
	v_exp_f32_e32 v77, v77
	v_add_f32_e32 v250, v74, v250
	v_exp_f32_e32 v78, v78
	v_add_f32_e32 v250, v75, v250
	v_exp_f32_e32 v79, v79
	v_add_f32_e32 v250, v76, v250
	v_add_f32_e32 v250, v77, v250
	v_add_f32_e32 v250, v78, v250
	v_add_f32_e32 v250, v79, v250
	s_and_b32 s2, s43, 3
	v_add_f32_e32 v172, v172, v250
	s_mov_b64 s[100:101], 0
	s_cmp_lg_u32 s2, 0
	s_cbranch_scc1 .Ldp_ck_done
	ds_bpermute_b32 v251, v147, v250
	s_waitcnt lgkmcnt(0)
	v_add_f32_e32 v250, v250, v251
	v_cmp_lt_f32_e32 vcc, s88, v250
	s_cbranch_vccz .Ldp_ck_done
	v_frexp_exp_i32_f32_e32 v251, v250
	v_add_u32_e32 v251, -7, v251
	v_cvt_f32_i32_e32 v251, v251
	s_mov_b64 s[100:101], -1
	v_cndmask_b32_e32 v251, 0, v251, vcc
	v_exp_f32_e64 v252, -v251
	v_add_f32_e32 v169, v169, v251
	v_mul_f32_e32 v172, v172, v252
.Ldp_ck_done:
	v_cvt_pk_bf16_f32 v64, v64, v65
	v_cvt_pk_bf16_f32 v65, v66, v67
	v_cvt_pk_bf16_f32 v66, v68, v69
	v_cvt_pk_bf16_f32 v67, v70, v71
	v_cvt_pk_bf16_f32 v68, v72, v73
	v_cvt_pk_bf16_f32 v69, v74, v75
	v_cvt_pk_bf16_f32 v70, v76, v77
	v_cvt_pk_bf16_f32 v71, v78, v79
	v_cvt_pk_bf16_f32 v72, v80, v81
	v_cvt_pk_bf16_f32 v73, v82, v83
	v_cvt_pk_bf16_f32 v74, v84, v85
	v_cvt_pk_bf16_f32 v75, v86, v87
	v_cvt_pk_bf16_f32 v76, v88, v89
	v_cvt_pk_bf16_f32 v77, v90, v91
	v_cvt_pk_bf16_f32 v78, v92, v93
	v_cvt_pk_bf16_f32 v79, v94, v95
	s_sub_i32 s45, s44, 63
	s_addk_i32 s44, 0x7f
	s_cmpk_gt_i32 s45, 0x7f
	s_cselect_b64 vcc, -1, 0
	s_cmpk_lt_i32 s44, 0xff81
	s_cselect_b64 s[2:3], -1, 0
	v_cndmask_b32_e64 v196, 0, v156, s[2:3]
	v_cndmask_b32_e32 v196, v196, v157, vcc
	v_sub_f32_e32 v196, v196, v169
	v_mov_b32_e32 v197, v196
	v_mov_b32_e32 v198, v196
	v_mov_b32_e32 v199, v196
	v_mov_b32_e32 v200, v196
	v_mov_b32_e32 v201, v196
	v_mov_b32_e32 v202, v196
	v_mov_b32_e32 v203, v196
	v_mov_b32_e32 v204, v196
	v_mov_b32_e32 v205, v196
	v_mov_b32_e32 v206, v196
	v_mov_b32_e32 v207, v196
	v_mov_b32_e32 v208, v196
	v_mov_b32_e32 v209, v196
	v_mov_b32_e32 v210, v196
	v_mov_b32_e32 v211, v196
	s_waitcnt lgkmcnt(0)
	s_nop 0
	v_mfma_f32_32x32x16_bf16 v[80:95], v[212:215], v[96:99], v[196:211]
	v_mfma_f32_32x32x16_bf16 v[196:211], v[216:219], v[96:99], v[196:211]
	v_mfma_f32_32x32x16_bf16 v[80:95], v[220:223], v[100:103], v[80:95]
	v_mfma_f32_32x32x16_bf16 v[196:211], v[224:227], v[100:103], v[196:211]
	v_mfma_f32_32x32x16_bf16 v[80:95], v[228:231], v[104:107], v[80:95]
	v_mfma_f32_32x32x16_bf16 v[196:211], v[232:235], v[104:107], v[196:211]
	v_mfma_f32_32x32x16_bf16 v[80:95], v[176:179], v[108:111], v[80:95]
	v_mfma_f32_32x32x16_bf16 v[196:211], v[242:245], v[108:111], v[196:211]
	s_cmpk_lt_i32 s45, 0x80
	s_cselect_b64 s[2:3], -1, 0
	s_cmpk_gt_i32 s44, 0xff80
	s_cselect_b64 s[44:45], -1, 0
	s_and_b64 s[2:3], s[2:3], s[44:45]
	s_andn2_b64 vcc, exec, s[2:3]
	s_cbranch_vccnz .Ldp_b1_skip
; DI void attn_diff_unit(const Params& p, int li, int b, int h, int qb, char* smem, bool pre, int nh, bool has_next) {
;     ...
;       if (relmin < 128 && relmax > -128) {
;         const int base = kbase - qpos + 255 + 4 * hh;
; #pragma unroll
;         for (int i = 0; i < 16; ++i) {
;           int i0 = base + (i & 3) + 8 * (i >> 2);
;           int i1 = i0 + 32;
;           i0 = i0 < 0 ? 0 : (i0 > 510 ? 510 : i0);
;           i1 = i1 < 0 ? 0 : (i1 > 510 ? 510 : i1);
;           s0[i] += tab[i0]; s1[i] += tab[i1];
;         }
;       }
	s_add_i32 s2, 0, 0x25000
	v_add_u32_e32 v212, 0x13f, v173
	v_add_u32_e32 v228, 0x13f, v173
	v_add_u32_e32 v213, 0x140, v173
	v_add_u32_e32 v229, 0x140, v173
	v_add_u32_e32 v214, 0x141, v173
	v_add_u32_e32 v230, 0x141, v173
	v_add_u32_e32 v215, 0x142, v173
	v_add_u32_e32 v231, 0x142, v173
	v_add_u32_e32 v216, 0x147, v173
	v_add_u32_e32 v232, 0x147, v173
	v_add_u32_e32 v217, 0x148, v173
	v_add_u32_e32 v233, 0x148, v173
	v_add_u32_e32 v218, 0x149, v173
	v_add_u32_e32 v234, 0x149, v173
	v_add_u32_e32 v219, 0x14a, v173
	v_add_u32_e32 v235, 0x14a, v173
	v_add_u32_e32 v220, 0x14f, v173
	v_add_u32_e32 v176, 0x14f, v173
	v_add_u32_e32 v221, 0x150, v173
	v_add_u32_e32 v177, 0x150, v173
	v_add_u32_e32 v222, 0x151, v173
	v_add_u32_e32 v178, 0x151, v173
	v_add_u32_e32 v223, 0x152, v173
	v_add_u32_e32 v179, 0x152, v173
	v_add_u32_e32 v224, 0x157, v173
	v_add_u32_e32 v242, 0x157, v173
	v_add_u32_e32 v225, 0x158, v173
	v_add_u32_e32 v243, 0x158, v173
	v_add_u32_e32 v226, 0x159, v173
	v_add_u32_e32 v244, 0x159, v173
	v_add_u32_e32 v227, 0x15a, v173
	v_add_u32_e32 v245, 0x15a, v173
	v_med3_i32 v212, v212, 0, v192
	v_med3_i32 v228, v228, s33, v193
	v_med3_i32 v213, v213, 0, v192
	v_med3_i32 v229, v229, s33, v193
	v_med3_i32 v214, v214, 0, v192
	v_med3_i32 v230, v230, s33, v193
	v_med3_i32 v215, v215, 0, v192
	v_med3_i32 v231, v231, s33, v193
	v_med3_i32 v216, v216, 0, v192
	v_med3_i32 v232, v232, s33, v193
	v_med3_i32 v217, v217, 0, v192
	v_med3_i32 v233, v233, s33, v193
	v_med3_i32 v218, v218, 0, v192
	v_med3_i32 v234, v234, s33, v193
	v_med3_i32 v219, v219, 0, v192
	v_med3_i32 v235, v235, s33, v193
	v_med3_i32 v220, v220, 0, v192
	v_med3_i32 v176, v176, s33, v193
	v_med3_i32 v221, v221, 0, v192
	v_med3_i32 v177, v177, s33, v193
	v_med3_i32 v222, v222, 0, v192
	v_med3_i32 v178, v178, s33, v193
	v_med3_i32 v223, v223, 0, v192
	v_med3_i32 v179, v179, s33, v193
	v_med3_i32 v224, v224, 0, v192
	v_med3_i32 v242, v242, s33, v193
	v_med3_i32 v225, v225, 0, v192
	v_med3_i32 v243, v243, s33, v193
	v_med3_i32 v226, v226, 0, v192
	v_med3_i32 v244, v244, s33, v193
	v_med3_i32 v227, v227, 0, v192
	v_med3_i32 v245, v245, s33, v193
	v_lshl_add_u32 v212, v212, 2, s2
	v_lshl_add_u32 v228, v228, 2, s2
	v_lshl_add_u32 v213, v213, 2, s2
	v_lshl_add_u32 v229, v229, 2, s2
	v_lshl_add_u32 v214, v214, 2, s2
	v_lshl_add_u32 v230, v230, 2, s2
	v_lshl_add_u32 v215, v215, 2, s2
	v_lshl_add_u32 v231, v231, 2, s2
	v_lshl_add_u32 v216, v216, 2, s2
	v_lshl_add_u32 v232, v232, 2, s2
	v_lshl_add_u32 v217, v217, 2, s2
	v_lshl_add_u32 v233, v233, 2, s2
	v_lshl_add_u32 v218, v218, 2, s2
	v_lshl_add_u32 v234, v234, 2, s2
	v_lshl_add_u32 v219, v219, 2, s2
	v_lshl_add_u32 v235, v235, 2, s2
	v_lshl_add_u32 v220, v220, 2, s2
	v_lshl_add_u32 v176, v176, 2, s2
	v_lshl_add_u32 v221, v221, 2, s2
	v_lshl_add_u32 v177, v177, 2, s2
	v_lshl_add_u32 v222, v222, 2, s2
	v_lshl_add_u32 v178, v178, 2, s2
	v_lshl_add_u32 v223, v223, 2, s2
	v_lshl_add_u32 v179, v179, 2, s2
	v_lshl_add_u32 v224, v224, 2, s2
	v_lshl_add_u32 v242, v242, 2, s2
	v_lshl_add_u32 v225, v225, 2, s2
	v_lshl_add_u32 v243, v243, 2, s2
	v_lshl_add_u32 v226, v226, 2, s2
	v_lshl_add_u32 v244, v244, 2, s2
	v_lshl_add_u32 v227, v227, 2, s2
	v_lshl_add_u32 v245, v245, 2, s2
	ds_read_b32 v212, v212
	ds_read_b32 v228, v228 offset:128
	ds_read_b32 v213, v213
	ds_read_b32 v229, v229 offset:128
	ds_read_b32 v214, v214
	ds_read_b32 v230, v230 offset:128
	ds_read_b32 v215, v215
	ds_read_b32 v231, v231 offset:128
	ds_read_b32 v216, v216
	ds_read_b32 v232, v232 offset:128
	ds_read_b32 v217, v217
	ds_read_b32 v233, v233 offset:128
	ds_read_b32 v218, v218
	ds_read_b32 v234, v234 offset:128
	ds_read_b32 v219, v219
	ds_read_b32 v235, v235 offset:128
	ds_read_b32 v220, v220
	ds_read_b32 v176, v176 offset:128
	ds_read_b32 v221, v221
	ds_read_b32 v177, v177 offset:128
	ds_read_b32 v222, v222
	ds_read_b32 v178, v178 offset:128
	ds_read_b32 v223, v223
	ds_read_b32 v179, v179 offset:128
	ds_read_b32 v224, v224
	ds_read_b32 v242, v242 offset:128
	ds_read_b32 v225, v225
	ds_read_b32 v243, v243 offset:128
	ds_read_b32 v226, v226
	ds_read_b32 v244, v244 offset:128
	ds_read_b32 v227, v227
	ds_read_b32 v245, v245 offset:128
	s_waitcnt lgkmcnt(0)
	v_add_f32_e32 v80, v80, v212
	v_add_f32_e32 v196, v196, v228
	v_add_f32_e32 v81, v81, v213
	v_add_f32_e32 v197, v197, v229
	v_add_f32_e32 v82, v82, v214
	v_add_f32_e32 v198, v198, v230
	v_add_f32_e32 v83, v83, v215
	v_add_f32_e32 v199, v199, v231
	v_add_f32_e32 v84, v84, v216
	v_add_f32_e32 v200, v200, v232
	v_add_f32_e32 v85, v85, v217
	v_add_f32_e32 v201, v201, v233
	v_add_f32_e32 v86, v86, v218
	v_add_f32_e32 v202, v202, v234
	v_add_f32_e32 v87, v87, v219
	v_add_f32_e32 v203, v203, v235
	v_add_f32_e32 v88, v88, v220
	v_add_f32_e32 v204, v204, v176
	v_add_f32_e32 v89, v89, v221
	v_add_f32_e32 v205, v205, v177
	v_add_f32_e32 v90, v90, v222
	v_add_f32_e32 v206, v206, v178
	v_add_f32_e32 v91, v91, v223
	v_add_f32_e32 v207, v207, v179
	v_add_f32_e32 v92, v92, v224
	v_add_f32_e32 v208, v208, v242
	v_add_f32_e32 v93, v93, v225
	v_add_f32_e32 v209, v209, v243
	v_add_f32_e32 v94, v94, v226
	v_add_f32_e32 v210, v210, v244
	v_add_f32_e32 v95, v95, v227
	v_add_f32_e32 v211, v211, v245
; DI f32x16 mfma32(bf16x8 a, bf16x8 b, f32x16 c) { return __builtin_amdgcn_mfma_f32_32x32x16_bf16(a, b, c, 0, 0, 0); }
; DI bool softmax_tile(f32x16& s0, f32x16& s1, float& m, float& l, float& alpha, bf16x8* pf, int lane, bool first, bool check) {
;     ...
;   float sum = 0.f;
; #pragma unroll
;   for (int i = 0; i < 16; ++i) { s0[i] = __builtin_amdgcn_exp2f(s0[i]); sum += s0[i]; }
; #pragma unroll
;   for (int i = 0; i < 16; ++i) { s1[i] = __builtin_amdgcn_exp2f(s1[i]); sum += s1[i]; }
;   l += sum;
;   pf[0] = pack8(s0, 0); pf[1] = pack8(s0, 8); pf[2] = pack8(s1, 0); pf[3] = pack8(s1, 8);
; DI void attn_diff_unit(const Params& p, int li, int b, int h, int qb, char* smem, bool pre, int nh, bool has_next) {
;     ...
;       float alpha; bf16x8 pf[4];
;       const bool resc = softmax_tile(s0, s1, m, l, alpha, pf, lane, (kt == 0) && (sub == 0), (sub == 0) && ((kt & 3) == 0));
;       {
;         bf16x8 vf[2][4];
; #pragma unroll
;         for (int j = 0; j < 4; ++j) vf[0][j] = ld_vfrag_tr(vs, vbase, VR, sub * 64, j * 32);
; #pragma unroll
;         for (int s = 0; s < 4; ++s) {
;           if (s < 3) {
; #pragma unroll
;             for (int j = 0; j < 4; ++j) vf[(s + 1) & 1][j] = ld_vfrag_tr(vs, vbase, VR, sub * 64 + 16 * (s + 1), j * 32);
;           }
;           __builtin_amdgcn_sched_barrier(0); __builtin_amdgcn_s_setprio(1);
; #pragma unroll
;           for (int j = 0; j < 4; ++j) O[j] = mfma32(vf[s & 1][j], pf[s], O[j]);
;         __builtin_amdgcn_s_setprio(0);
; }
;       }
.Ldp_b1_skip:
	ds_read_b64_tr_b16 v[212:213], v175 offset:34816
	ds_read_b64_tr_b16 v[214:215], v175 offset:37376
	ds_read_b64_tr_b16 v[216:217], v175 offset:34880
	ds_read_b64_tr_b16 v[218:219], v175 offset:37440
	ds_read_b64_tr_b16 v[220:221], v175 offset:34944
	ds_read_b64_tr_b16 v[222:223], v175 offset:37504
	ds_read_b64_tr_b16 v[224:225], v175 offset:35008
	ds_read_b64_tr_b16 v[226:227], v175 offset:37568
	ds_read_b64_tr_b16 v[228:229], v175 offset:39936
	ds_read_b64_tr_b16 v[230:231], v175 offset:42496
	ds_read_b64_tr_b16 v[232:233], v175 offset:40000
	ds_read_b64_tr_b16 v[234:235], v175 offset:42560
	s_waitcnt lgkmcnt(10)
	v_mfma_f32_32x32x16_bf16 v[48:63], v[212:215], v[72:75], v[48:63]
	v_exp_f32_e32 v80, v80
	v_exp_f32_e32 v81, v81
	s_waitcnt lgkmcnt(8)
	v_mfma_f32_32x32x16_bf16 v[32:47], v[216:219], v[72:75], v[32:47]
	v_exp_f32_e32 v82, v82
	v_exp_f32_e32 v83, v83
	v_add_f32_e32 v253, 0, v80
	v_add_f32_e32 v253, v81, v253
	s_waitcnt lgkmcnt(6)
	v_mfma_f32_32x32x16_bf16 v[16:31], v[220:223], v[72:75], v[16:31]
	v_exp_f32_e32 v84, v84
	v_exp_f32_e32 v85, v85
	v_add_f32_e32 v253, v82, v253
	v_add_f32_e32 v253, v83, v253
	s_waitcnt lgkmcnt(4)
	v_mfma_f32_32x32x16_bf16 v[0:15], v[224:227], v[72:75], v[0:15]
	v_exp_f32_e32 v86, v86
	v_exp_f32_e32 v87, v87
	v_add_f32_e32 v253, v84, v253
	v_add_f32_e32 v253, v85, v253
	ds_read_b64_tr_b16 v[176:177], v175 offset:40064
	ds_read_b64_tr_b16 v[178:179], v175 offset:42624
	ds_read_b64_tr_b16 v[242:243], v175 offset:40128
	ds_read_b64_tr_b16 v[244:245], v175 offset:42688
	ds_read_b64_tr_b16 v[212:213], v175 offset:45056
	ds_read_b64_tr_b16 v[214:215], v175 offset:47616
	ds_read_b64_tr_b16 v[216:217], v175 offset:45120
	ds_read_b64_tr_b16 v[218:219], v175 offset:47680
	s_waitcnt lgkmcnt(10)
	v_mfma_f32_32x32x16_bf16 v[48:63], v[228:231], v[76:79], v[48:63]
	v_exp_f32_e32 v88, v88
	v_exp_f32_e32 v89, v89
	v_add_f32_e32 v253, v86, v253
	v_add_f32_e32 v253, v87, v253
	v_cvt_pk_bf16_f32 v80, v80, v81
	s_waitcnt lgkmcnt(8)
	v_mfma_f32_32x32x16_bf16 v[32:47], v[232:235], v[76:79], v[32:47]
	v_exp_f32_e32 v90, v90
	v_exp_f32_e32 v91, v91
	v_add_f32_e32 v253, v88, v253
	v_add_f32_e32 v253, v89, v253
	v_cvt_pk_bf16_f32 v81, v82, v83
	s_waitcnt lgkmcnt(6)
	v_mfma_f32_32x32x16_bf16 v[16:31], v[176:179], v[76:79], v[16:31]
	v_exp_f32_e32 v92, v92
	v_exp_f32_e32 v93, v93
	v_add_f32_e32 v253, v90, v253
	v_add_f32_e32 v253, v91, v253
	v_cvt_pk_bf16_f32 v82, v84, v85
	s_waitcnt lgkmcnt(4)
	v_mfma_f32_32x32x16_bf16 v[0:15], v[242:245], v[76:79], v[0:15]
	v_exp_f32_e32 v94, v94
	v_exp_f32_e32 v95, v95
	v_add_f32_e32 v253, v92, v253
	v_add_f32_e32 v253, v93, v253
	v_cvt_pk_bf16_f32 v83, v86, v87
	ds_read_b64_tr_b16 v[220:221], v175 offset:45184
	ds_read_b64_tr_b16 v[222:223], v175 offset:47744
	ds_read_b64_tr_b16 v[224:225], v175 offset:45248
	ds_read_b64_tr_b16 v[226:227], v175 offset:47808
	ds_read_b64_tr_b16 v[228:229], v175 offset:50176
	ds_read_b64_tr_b16 v[230:231], v175 offset:52736
	ds_read_b64_tr_b16 v[232:233], v175 offset:50240
	ds_read_b64_tr_b16 v[234:235], v175 offset:52800
	s_waitcnt lgkmcnt(10)
	v_mfma_f32_32x32x16_bf16 v[48:63], v[212:215], v[64:67], v[48:63]
	v_exp_f32_e32 v196, v196
	v_exp_f32_e32 v197, v197
	v_add_f32_e32 v253, v94, v253
	v_add_f32_e32 v253, v95, v253
	v_cvt_pk_bf16_f32 v84, v88, v89
	s_waitcnt lgkmcnt(8)
	v_mfma_f32_32x32x16_bf16 v[32:47], v[216:219], v[64:67], v[32:47]
	v_exp_f32_e32 v198, v198
	v_exp_f32_e32 v199, v199
	v_add_f32_e32 v253, v196, v253
	v_add_f32_e32 v253, v197, v253
	v_cvt_pk_bf16_f32 v85, v90, v91
	s_waitcnt lgkmcnt(6)
	v_mfma_f32_32x32x16_bf16 v[16:31], v[220:223], v[64:67], v[16:31]
	v_exp_f32_e32 v200, v200
	v_exp_f32_e32 v201, v201
	v_add_f32_e32 v253, v198, v253
	v_add_f32_e32 v253, v199, v253
	v_cvt_pk_bf16_f32 v86, v92, v93
	s_waitcnt lgkmcnt(4)
	v_mfma_f32_32x32x16_bf16 v[0:15], v[224:227], v[64:67], v[0:15]
	v_exp_f32_e32 v202, v202
	v_exp_f32_e32 v203, v203
	v_add_f32_e32 v253, v200, v253
	v_add_f32_e32 v253, v201, v253
	v_cvt_pk_bf16_f32 v87, v94, v95
	ds_read_b64_tr_b16 v[176:177], v175 offset:50304
	ds_read_b64_tr_b16 v[178:179], v175 offset:52864
	ds_read_b64_tr_b16 v[242:243], v175 offset:50368
	ds_read_b64_tr_b16 v[244:245], v175 offset:52928
	s_waitcnt lgkmcnt(6)
	v_mfma_f32_32x32x16_bf16 v[48:63], v[228:231], v[68:71], v[48:63]
	v_exp_f32_e32 v204, v204
	v_exp_f32_e32 v205, v205
	v_add_f32_e32 v253, v202, v253
	v_add_f32_e32 v253, v203, v253
	v_cvt_pk_bf16_f32 v196, v196, v197
	s_waitcnt lgkmcnt(4)
	v_mfma_f32_32x32x16_bf16 v[32:47], v[232:235], v[68:71], v[32:47]
	v_exp_f32_e32 v206, v206
	v_exp_f32_e32 v207, v207
	v_add_f32_e32 v253, v204, v253
	v_add_f32_e32 v253, v205, v253
	v_cvt_pk_bf16_f32 v197, v198, v199
	s_waitcnt lgkmcnt(2)
	v_mfma_f32_32x32x16_bf16 v[16:31], v[176:179], v[68:71], v[16:31]
	v_exp_f32_e32 v208, v208
	v_exp_f32_e32 v209, v209
	v_add_f32_e32 v253, v206, v253
	v_add_f32_e32 v253, v207, v253
	v_cvt_pk_bf16_f32 v198, v200, v201
	s_waitcnt lgkmcnt(0)
	v_mfma_f32_32x32x16_bf16 v[0:15], v[242:245], v[68:71], v[0:15]
	v_exp_f32_e32 v210, v210
	v_exp_f32_e32 v211, v211
	v_add_f32_e32 v253, v208, v253
	v_add_f32_e32 v253, v209, v253
	v_cvt_pk_bf16_f32 v199, v202, v203
	v_add_f32_e32 v253, v210, v253
	v_add_f32_e32 v253, v211, v253
	v_cvt_pk_bf16_f32 v200, v204, v205
	v_cvt_pk_bf16_f32 v201, v206, v207
	v_cvt_pk_bf16_f32 v202, v208, v209
	v_cvt_pk_bf16_f32 v203, v210, v211
	v_add_f32_e32 v172, v172, v253
	s_andn2_b64 vcc, exec, s[100:101]
	s_cbranch_vccnz .Ldp_nors
; DI f32x16 mfma32(bf16x8 a, bf16x8 b, f32x16 c) { return __builtin_amdgcn_mfma_f32_32x32x16_bf16(a, b, c, 0, 0, 0); }
; DI void attn_diff_unit(const Params& p, int li, int b, int h, int qb, char* smem, bool pre, int nh, bool has_next) {
;     ...
;       {
;         bf16x8 vf[2][4];
; #pragma unroll
;         for (int j = 0; j < 4; ++j) vf[0][j] = ld_vfrag_tr(vs, vbase, VR, sub * 64, j * 32);
; #pragma unroll
;         for (int s = 0; s < 4; ++s) {
;           if (s < 3) {
; #pragma unroll
;             for (int j = 0; j < 4; ++j) vf[(s + 1) & 1][j] = ld_vfrag_tr(vs, vbase, VR, sub * 64 + 16 * (s + 1), j * 32);
;           }
;           __builtin_amdgcn_sched_barrier(0); __builtin_amdgcn_s_setprio(1);
; #pragma unroll
;           for (int j = 0; j < 4; ++j) O[j] = mfma32(vf[s & 1][j], pf[s], O[j]);
;         __builtin_amdgcn_s_setprio(0);
; }
;       }
;       if (resc) {
; #pragma unroll
;         for (int j = 0; j < 4; ++j) scale16(O[j], alpha);
;       }
;     }
;     if (kt + 1 < 32) put_stage(smem + ((kt + 1) & 1) * STG);
;     else if (has_next) put_stage(smem);
;     __syncthreads();
	s_nop 15
	v_mul_f32_e32 v0, v0, v252
	v_mul_f32_e32 v1, v1, v252
	v_mul_f32_e32 v2, v2, v252
	v_mul_f32_e32 v3, v3, v252
	v_mul_f32_e32 v4, v4, v252
	v_mul_f32_e32 v5, v5, v252
	v_mul_f32_e32 v6, v6, v252
	v_mul_f32_e32 v7, v7, v252
	v_mul_f32_e32 v8, v8, v252
	v_mul_f32_e32 v9, v9, v252
	v_mul_f32_e32 v10, v10, v252
	v_mul_f32_e32 v11, v11, v252
	v_mul_f32_e32 v12, v12, v252
	v_mul_f32_e32 v13, v13, v252
	v_mul_f32_e32 v14, v14, v252
	v_mul_f32_e32 v15, v15, v252
	v_mul_f32_e32 v16, v16, v252
	v_mul_f32_e32 v17, v17, v252
	v_mul_f32_e32 v18, v18, v252
	v_mul_f32_e32 v19, v19, v252
	v_mul_f32_e32 v20, v20, v252
	v_mul_f32_e32 v21, v21, v252
	v_mul_f32_e32 v22, v22, v252
	v_mul_f32_e32 v23, v23, v252
	v_mul_f32_e32 v24, v24, v252
	v_mul_f32_e32 v25, v25, v252
	v_mul_f32_e32 v26, v26, v252
	v_mul_f32_e32 v27, v27, v252
	v_mul_f32_e32 v28, v28, v252
	v_mul_f32_e32 v29, v29, v252
	v_mul_f32_e32 v30, v30, v252
	v_mul_f32_e32 v31, v31, v252
	v_mul_f32_e32 v32, v32, v252
	v_mul_f32_e32 v33, v33, v252
	v_mul_f32_e32 v34, v34, v252
	v_mul_f32_e32 v35, v35, v252
	v_mul_f32_e32 v36, v36, v252
	v_mul_f32_e32 v37, v37, v252
	v_mul_f32_e32 v38, v38, v252
	v_mul_f32_e32 v39, v39, v252
	v_mul_f32_e32 v40, v40, v252
	v_mul_f32_e32 v41, v41, v252
	v_mul_f32_e32 v42, v42, v252
	v_mul_f32_e32 v43, v43, v252
	v_mul_f32_e32 v44, v44, v252
	v_mul_f32_e32 v45, v45, v252
	v_mul_f32_e32 v46, v46, v252
	v_mul_f32_e32 v47, v47, v252
	v_mul_f32_e32 v48, v48, v252
	v_mul_f32_e32 v49, v49, v252
	v_mul_f32_e32 v50, v50, v252
	v_mul_f32_e32 v51, v51, v252
	v_mul_f32_e32 v52, v52, v252
	v_mul_f32_e32 v53, v53, v252
	v_mul_f32_e32 v54, v54, v252
	v_mul_f32_e32 v55, v55, v252
	v_mul_f32_e32 v56, v56, v252
	v_mul_f32_e32 v57, v57, v252
	v_mul_f32_e32 v58, v58, v252
	v_mul_f32_e32 v59, v59, v252
	v_mul_f32_e32 v60, v60, v252
	v_mul_f32_e32 v61, v61, v252
	v_mul_f32_e32 v62, v62, v252
	v_mul_f32_e32 v63, v63, v252
.Ldp_nors:
	ds_read_b64_tr_b16 v[212:213], v175 offset:55296
	ds_read_b64_tr_b16 v[214:215], v175 offset:57856
	ds_read_b64_tr_b16 v[216:217], v175 offset:55360
	ds_read_b64_tr_b16 v[218:219], v175 offset:57920
	ds_read_b64_tr_b16 v[220:221], v175 offset:55424
	ds_read_b64_tr_b16 v[222:223], v175 offset:57984
	ds_read_b64_tr_b16 v[224:225], v175 offset:55488
	ds_read_b64_tr_b16 v[226:227], v175 offset:58048
	ds_read_b64_tr_b16 v[228:229], v175 offset:60416
	ds_read_b64_tr_b16 v[230:231], v175 offset:62976
	ds_read_b64_tr_b16 v[232:233], v175 offset:60480
	ds_read_b64_tr_b16 v[234:235], v175 offset:63040
	s_waitcnt lgkmcnt(10)
	v_mfma_f32_32x32x16_bf16 v[48:63], v[212:215], v[80:83], v[48:63]
	s_waitcnt lgkmcnt(8)
	v_mfma_f32_32x32x16_bf16 v[32:47], v[216:219], v[80:83], v[32:47]
	s_waitcnt lgkmcnt(6)
	v_mfma_f32_32x32x16_bf16 v[16:31], v[220:223], v[80:83], v[16:31]
	s_waitcnt lgkmcnt(4)
	v_mfma_f32_32x32x16_bf16 v[0:15], v[224:227], v[80:83], v[0:15]
	ds_read_b64_tr_b16 v[176:177], v175 offset:60544
	ds_read_b64_tr_b16 v[178:179], v175 offset:63104
	ds_read_b64_tr_b16 v[242:243], v175 offset:60608
	ds_read_b64_tr_b16 v[244:245], v175 offset:63168
	ds_read_b64_tr_b16 v[212:213], v236 offset:30720
	ds_read_b64_tr_b16 v[214:215], v236 offset:33280
	ds_read_b64_tr_b16 v[216:217], v236 offset:30784
	ds_read_b64_tr_b16 v[218:219], v236 offset:33344
	s_waitcnt lgkmcnt(10)
	v_mfma_f32_32x32x16_bf16 v[48:63], v[228:231], v[84:87], v[48:63]
	s_waitcnt lgkmcnt(8)
	v_mfma_f32_32x32x16_bf16 v[32:47], v[232:235], v[84:87], v[32:47]
	s_waitcnt lgkmcnt(6)
	v_mfma_f32_32x32x16_bf16 v[16:31], v[176:179], v[84:87], v[16:31]
	s_waitcnt lgkmcnt(4)
	v_mfma_f32_32x32x16_bf16 v[0:15], v[242:245], v[84:87], v[0:15]
	ds_read_b64_tr_b16 v[220:221], v236 offset:30848
	ds_read_b64_tr_b16 v[222:223], v236 offset:33408
	ds_read_b64_tr_b16 v[224:225], v236 offset:30912
	ds_read_b64_tr_b16 v[226:227], v236 offset:33472
	ds_read_b64_tr_b16 v[228:229], v236 offset:35840
	ds_read_b64_tr_b16 v[230:231], v236 offset:38400
	ds_read_b64_tr_b16 v[232:233], v236 offset:35904
	ds_read_b64_tr_b16 v[234:235], v236 offset:38464
	s_waitcnt lgkmcnt(10)
	v_mfma_f32_32x32x16_bf16 v[48:63], v[212:215], v[196:199], v[48:63]
	s_waitcnt lgkmcnt(8)
	v_mfma_f32_32x32x16_bf16 v[32:47], v[216:219], v[196:199], v[32:47]
	s_waitcnt lgkmcnt(6)
	v_mfma_f32_32x32x16_bf16 v[16:31], v[220:223], v[196:199], v[16:31]
	s_waitcnt lgkmcnt(4)
	v_mfma_f32_32x32x16_bf16 v[0:15], v[224:227], v[196:199], v[0:15]
	ds_read_b64_tr_b16 v[176:177], v236 offset:35968
	ds_read_b64_tr_b16 v[178:179], v236 offset:38528
	ds_read_b64_tr_b16 v[242:243], v236 offset:36032
	ds_read_b64_tr_b16 v[244:245], v236 offset:38592
	s_waitcnt lgkmcnt(6)
	v_mfma_f32_32x32x16_bf16 v[48:63], v[228:231], v[200:203], v[48:63]
	s_waitcnt lgkmcnt(4)
	v_mfma_f32_32x32x16_bf16 v[32:47], v[232:235], v[200:203], v[32:47]
	s_waitcnt lgkmcnt(2)
	v_mfma_f32_32x32x16_bf16 v[16:31], v[176:179], v[200:203], v[16:31]
	s_waitcnt lgkmcnt(0)
	v_mfma_f32_32x32x16_bf16 v[0:15], v[242:245], v[200:203], v[0:15]
	s_add_i32 s44, s43, 1
	s_cmpk_eq_i32 s24, 0xf80
	s_mov_b64 s[2:3], -1
	s_cbranch_scc1 .LBB0_583
	s_bitcmp1_b32 s44, 0
	s_cselect_b32 s2, 0x12800, 0
	s_add_i32 s2, s2, 0
	v_add3_u32 v64, s2, v161, v159
	v_add3_u32 v65, s2, v160, v159
	s_mov_b64 s[2:3], 0
	s_waitcnt vmcnt(3)
	ds_write_b128 v64, v[116:119]
	v_add_u32_e32 v66, 0x8800, v65
	s_waitcnt vmcnt(1)
	ds_write_b128 v65, v[128:131] offset:34816
	s_waitcnt vmcnt(5)
	ds_write_b128 v64, v[112:115] offset:8704
	s_waitcnt vmcnt(4)
	ds_write_b128 v65, v[120:123] offset:45056
	s_waitcnt vmcnt(3)
	ds_write_b128 v64, v[124:127] offset:17408
	s_waitcnt vmcnt(2)
	ds_write_b128 v65, v[132:135] offset:55296
	s_waitcnt vmcnt(1)
	ds_write_b128 v64, v[136:139] offset:26112
	s_waitcnt vmcnt(0)
	ds_write_b128 v66, v[140:143] offset:30720

; DI bool softmax_tile(f32x16& s0, f32x16& s1, float& m, float& l, float& alpha, bf16x8* pf, int lane, bool first, bool check) {
;     ...
;   l += sum;
; DI void attn_diff_unit(const Params& p, int li, int b, int h, int qb, char* smem, bool pre, int nh, bool has_next) {
;     ...
;     if (kt + 1 < 32) put_stage(smem + ((kt + 1) & 1) * STG);
;     else if (has_next) put_stage(smem);
;     __syncthreads();
;     if (kt + 2 < 32) get_stage(kt + 2);
;     else if (kt == 30 && has_next) { gk += (nh - h) * 128; gv += (nh - h) * 128; get_stage(0); }
;   }
.LBB0_592:
	s_addk_i32 s24, 0x80
	s_add_u32 s34, s34, 0x40000
	s_addc_u32 s35, s35, 0
	s_cmpk_eq_i32 s24, 0x1000
	s_cbranch_scc1 .LBB0_594
	s_mov_b32 s43, s44
	v_mov_b64_e32 v[148:149], v[64:65]
	v_mov_b64_e32 v[150:151], v[66:67]
	s_branch .LBB0_568

; __global__ void __launch_bounds__(512) mega(Params p, int ph_lo, int ph_hi) {
;   extern __shared__ __attribute__((aligned(16))) unsigned char lds_raw[];
	.amdhsa_kernel _Z4mega6Paramsii
		.amdhsa_group_segment_fixed_size 0
		.amdhsa_private_segment_fixed_size 0
		.amdhsa_kernarg_size 448
		.amdhsa_user_sgpr_count 2
		.amdhsa_user_sgpr_dispatch_ptr 0
		.amdhsa_user_sgpr_queue_ptr 0
		.amdhsa_user_sgpr_kernarg_segment_ptr 1
		.amdhsa_user_sgpr_dispatch_id 0
		.amdhsa_user_sgpr_kernarg_preload_length 0
		.amdhsa_user_sgpr_kernarg_preload_offset 0
		.amdhsa_user_sgpr_private_segment_size 0
		.amdhsa_uses_dynamic_stack 0
		.amdhsa_enable_private_segment 0
		.amdhsa_system_sgpr_workgroup_id_x 1
		.amdhsa_system_sgpr_workgroup_id_y 0
		.amdhsa_system_sgpr_workgroup_id_z 0
		.amdhsa_system_sgpr_workgroup_info 0
		.amdhsa_system_vgpr_workitem_id 2
		.amdhsa_next_free_vgpr 256
		.amdhsa_next_free_sgpr 102
		.amdhsa_accum_offset 256
		.amdhsa_reserve_vcc 1
		.amdhsa_float_round_mode_32 0
		.amdhsa_float_round_mode_16_64 0
		.amdhsa_float_denorm_mode_32 3
		.amdhsa_float_denorm_mode_16_64 3
		.amdhsa_dx10_clamp 1
		.amdhsa_ieee_mode 1
		.amdhsa_fp16_overflow 0
		.amdhsa_tg_split 0
		.amdhsa_exception_fp_ieee_invalid_op 0
		.amdhsa_exception_fp_denorm_src 0
		.amdhsa_exception_fp_ieee_div_zero 0
		.amdhsa_exception_fp_ieee_overflow 0
		.amdhsa_exception_fp_ieee_underflow 0
		.amdhsa_exception_fp_ieee_inexact 0
		.amdhsa_exception_int_div_zero 0
	.end_amdhsa_kernel

; __global__ void __launch_bounds__(512) mega(Params p, int ph_lo, int ph_hi) {
.Lfunc_end0:
	.size	_Z4mega6Paramsii, .Lfunc_end0-_Z4mega6Paramsii
	.set _Z4mega6Paramsii.num_vgpr, 256
	.set _Z4mega6Paramsii.num_agpr, 0
	.set _Z4mega6Paramsii.numbered_sgpr, 102
	.set _Z4mega6Paramsii.num_named_barrier, 0
	.set _Z4mega6Paramsii.private_seg_size, 0
	.set _Z4mega6Paramsii.uses_vcc, 1
	.set _Z4mega6Paramsii.uses_flat_scratch, 0
	.set _Z4mega6Paramsii.has_dyn_sized_stack, 0
	.set _Z4mega6Paramsii.has_recursion, 0
	.set _Z4mega6Paramsii.has_indirect_call, 0

; __global__ void __launch_bounds__(512) mega(Params p, int ph_lo, int ph_hi) {
amdhsa.kernels:
  - .agpr_count:     0
    .args:
      - .offset:         0
        .size:           184
        .value_kind:     by_value
      - .offset:         184
        .size:           4
        .value_kind:     by_value
      - .offset:         188
        .size:           4
        .value_kind:     by_value
      - .offset:         192
        .size:           4
        .value_kind:     hidden_block_count_x
      - .offset:         196
        .size:           4
        .value_kind:     hidden_block_count_y
      - .offset:         200
        .size:           4
        .value_kind:     hidden_block_count_z
      - .offset:         204
        .size:           2
        .value_kind:     hidden_group_size_x
      - .offset:         206
        .size:           2
        .value_kind:     hidden_group_size_y
      - .offset:         208
        .size:           2
        .value_kind:     hidden_group_size_z
      - .offset:         210
        .size:           2
        .value_kind:     hidden_remainder_x
      - .offset:         212
        .size:           2
        .value_kind:     hidden_remainder_y
      - .offset:         214
        .size:           2
        .value_kind:     hidden_remainder_z
      - .offset:         232
        .size:           8
        .value_kind:     hidden_global_offset_x
      - .offset:         240
        .size:           8
        .value_kind:     hidden_global_offset_y
      - .offset:         248
        .size:           8
        .value_kind:     hidden_global_offset_z
      - .offset:         256
        .size:           2
        .value_kind:     hidden_grid_dims
      - .offset:         280
        .size:           8
        .value_kind:     hidden_multigrid_sync_arg
      - .offset:         312
        .size:           4
        .value_kind:     hidden_dynamic_lds_size
    .group_segment_fixed_size: 0
    .kernarg_segment_align: 8
    .kernarg_segment_size: 448
    .language:       OpenCL C
    .language_version:
      - 2
      - 0
    .max_flat_workgroup_size: 512
    .name:           _Z4mega6Paramsii
    .private_segment_fixed_size: 0
    .sgpr_count:     108
    .sgpr_spill_count: 294
    .symbol:         _Z4mega6Paramsii.kd
    .uniform_work_group_size: 1
    .uses_dynamic_stack: false
    .vgpr_count:     256
    .vgpr_spill_count: 0
    .wavefront_size: 64
